# mlstm2: next chunk's K / Q / XM rows touched right after the current chunk's loads are consumed (retire during compute; real loads then hit L2)
# baseline (speedup 1.0000x reference)
; __device__ __forceinline__ u16 f2bf(float f) { return (u16)(pk2(f, 0.f) & 0xffffu); }
; __device__ __forceinline__ float bflo(unsigned w) { return __uint_as_float(w << 16); }
; __device__ __forceinline__ float bfhi(unsigned w) { return __uint_as_float(w & 0xffff0000u); }
; __device__ void mlstm2_phase(const Params& p, unsigned char* smem) {
;     ...
;             for (int i = 0; i < 8; ++i) { const int idx = tid + 512 * i, r = idx >> 5, cc = (idx & 31) * 8;
;                 *(u32x4*)(Ks + r * 264 + cc) = *(const u32x4*)(KX + (size_t)(row0 + r) * 2048 + 256 * h + cc); }
;             bf16x8 qf[8];
; #pragma unroll
;             for (int ks = 0; ks < 8; ++ks) qf[ks] = *(const bf16x8*)(Q + (size_t)(row0 + 16 * wave + l15) * 2048 + 256 * h + 32 * ks + 8 * lq);
;             float vv[2][4];
; #pragma unroll
;             for (int i = 0; i < 2; ++i) { const int t = (tid + 512 * i) >> 3; const u32x2 raw = *(const u32x2*)(XM + (size_t)(row0 + t) * 2048 + vc);
;                 const float x0 = bflo(raw.x), x1 = bfhi(raw.x), x2 = bflo(raw.y), x3 = bfhi(raw.y);
; #pragma unroll
;                 for (int jj = 0; jj < 4; ++jj) vv[i][jj] = x0 * wvp[jj] + x1 * wvp[4 + jj] + x2 * wvp[8 + jj] + x3 * wvp[12 + jj]; }
;     ...
;             __syncthreads();
;             if (tid == 0) gS[1] = m_new;
; #pragma unroll
;             for (int i = 0; i < 2; ++i) { const int t = (tid + 512 * i) >> 3; const float w = gW[t];
; #pragma unroll
;                 for (int jj = 0; jj < 4; ++jj) { const int dv = 4 * (tid & 7) + jj; Vt[dv * 136 + t] = f2bf(vv[i][jj]); Vwt[dv * 136 + t] = f2bf(vv[i][jj] * w); } }
;             if (tid < 128) Vwt[32 * 136 + tid] = f2bf(gW[tid]);
.LBB0_427:
	s_waitcnt lgkmcnt(0)
	s_barrier
	s_and_saveexec_b64 s[52:53], s[2:3]
	v_mov_b32_e32 v79, s33
	ds_write_b32 v79, v78
	s_or_b64 exec, exec, s[52:53]
	s_waitcnt vmcnt(5)
	v_lshlrev_b32_e32 v78, 16, v76
	v_and_b32_e32 v76, 0xffff0000, v76
	s_waitcnt vmcnt(2)
	v_mul_f32_e32 v80, v70, v76
	v_mul_f32_e32 v81, v71, v76
	v_mul_f32_e32 v82, v72, v76
	v_mul_f32_e32 v76, v73, v76
	v_lshlrev_b32_e32 v79, 16, v77
	s_waitcnt vmcnt(1)
	v_fmac_f32_e32 v80, v66, v78
	v_fmac_f32_e32 v81, v67, v78
	v_fmac_f32_e32 v82, v68, v78
	v_fmac_f32_e32 v76, v69, v78
	v_and_b32_e32 v77, 0xffff0000, v77
	v_fmac_f32_e32 v80, v62, v79
	v_fmac_f32_e32 v81, v63, v79
	v_fmac_f32_e32 v82, v64, v79
	v_fmac_f32_e32 v76, v65, v79
	v_fmac_f32_e32 v80, v58, v77
	v_fmac_f32_e32 v81, v59, v77
	v_fmac_f32_e32 v82, v60, v77
	v_fmac_f32_e32 v76, v61, v77
	s_waitcnt vmcnt(0)
	v_add_u32_e32 v98, s79, v235
	v_add_u32_e32 v98, 128, v98
	v_ashrrev_i32_e32 v99, 31, v98
	v_lshlrev_b64 v[98:99], 12, v[98:99]
	v_lshl_add_u64 v[98:99], v[102:103], 0, v[98:99]
	global_load_dword v218, v[98:99], off
	v_add_u32_e32 v98, s79, v238
	v_add_u32_e32 v98, 128, v98
	v_ashrrev_i32_e32 v99, 31, v98
	v_lshlrev_b64 v[98:99], 12, v[98:99]
	v_lshl_add_u64 v[98:99], v[102:103], 0, v[98:99]
	global_load_dword v218, v[98:99], off
	v_add_u32_e32 v98, s79, v235
	v_add_u32_e32 v98, 160, v98
	v_ashrrev_i32_e32 v99, 31, v98
	v_lshlrev_b64 v[98:99], 12, v[98:99]
	v_lshl_add_u64 v[98:99], v[102:103], 0, v[98:99]
	global_load_dword v218, v[98:99], off
	v_add_u32_e32 v98, s79, v237
	v_add_u32_e32 v98, 128, v98
	v_ashrrev_i32_e32 v99, 31, v98
	v_lshlrev_b64 v[98:99], 12, v[98:99]
	v_lshl_add_u64 v[98:99], v[102:103], 0, v[98:99]
	global_load_dword v218, v[98:99], off
	v_add_u32_e32 v98, s79, v235
	v_add_u32_e32 v98, 192, v98
	v_ashrrev_i32_e32 v99, 31, v98
	v_lshlrev_b64 v[98:99], 12, v[98:99]
	v_lshl_add_u64 v[98:99], v[102:103], 0, v[98:99]
	global_load_dword v218, v[98:99], off
	v_add_u32_e32 v98, s79, v236
	v_add_u32_e32 v98, 128, v98
	v_ashrrev_i32_e32 v99, 31, v98
	v_lshlrev_b64 v[98:99], 12, v[98:99]
	v_lshl_add_u64 v[98:99], v[102:103], 0, v[98:99]
	global_load_dword v218, v[98:99], off
	v_add_u32_e32 v98, s79, v235
	v_add_u32_e32 v98, 224, v98
	v_ashrrev_i32_e32 v99, 31, v98
	v_lshlrev_b64 v[98:99], 12, v[98:99]
	v_lshl_add_u64 v[98:99], v[102:103], 0, v[98:99]
	global_load_dword v218, v[98:99], off
	v_add_u32_e32 v98, s79, v234
	v_add_u32_e32 v98, 128, v98
	v_ashrrev_i32_e32 v99, 31, v98
	v_lshlrev_b64 v[98:99], 12, v[98:99]
	v_lshl_add_u64 v[98:99], v[102:103], 0, v[98:99]
	global_load_dword v218, v[98:99], off
	v_add_u32_e32 v98, s79, v233
	v_add_u32_e32 v98, 128, v98
	v_ashrrev_i32_e32 v99, 31, v98
	v_lshlrev_b64 v[98:99], 12, v[98:99]
	v_lshl_add_u64 v[98:99], v[104:105], 0, v[98:99]
	global_load_dword v218, v[98:99], off
	global_load_dword v218, v[98:99], off offset:64
	global_load_dword v218, v[98:99], off offset:128
	global_load_dword v218, v[98:99], off offset:192
	global_load_dword v218, v[98:99], off offset:256
	global_load_dword v218, v[98:99], off offset:320
	global_load_dword v218, v[98:99], off offset:384
	global_load_dword v218, v[98:99], off offset:448
	v_add_u32_e32 v98, s79, v232
	v_add_u32_e32 v98, 128, v98
	v_ashrrev_i32_e32 v99, 31, v98
	v_lshlrev_b64 v[98:99], 12, v[98:99]
	v_lshl_add_u64 v[98:99], v[106:107], 0, v[98:99]
	global_load_dword v218, v[98:99], off
	v_add_u32_e32 v98, s79, v231
	v_add_u32_e32 v98, 128, v98
	v_ashrrev_i32_e32 v99, 31, v98
	v_lshlrev_b64 v[98:99], 12, v[98:99]
	v_lshl_add_u64 v[98:99], v[106:107], 0, v[98:99]
	global_load_dword v218, v[98:99], off
	v_lshlrev_b32_e32 v77, 16, v74
	v_and_b32_e32 v74, 0xffff0000, v74
	v_mul_f32_e32 v70, v70, v74
	v_lshlrev_b32_e32 v78, 16, v75
	v_fmac_f32_e32 v70, v66, v77
	v_fmac_f32_e32 v70, v62, v78
	ds_read_b32 v62, v132
	v_and_b32_e32 v75, 0xffff0000, v75
	v_fmac_f32_e32 v70, v58, v75
	v_mul_f32_e32 v58, v71, v74
	v_fmac_f32_e32 v58, v67, v77
	v_fmac_f32_e32 v58, v63, v78
	v_cvt_pk_bf16_f32 v63, v80, v93
	ds_write_b16 v133, v63
	s_waitcnt lgkmcnt(1)
	v_mul_f32_e32 v63, v80, v62
	v_cvt_pk_bf16_f32 v63, v63, v93
	ds_write_b16 v134, v63
	v_cvt_pk_bf16_f32 v63, v81, v93
	ds_write_b16 v135, v63
	v_mul_f32_e32 v63, v81, v62
	v_cvt_pk_bf16_f32 v63, v63, v93
	ds_write_b16 v136, v63
	v_cvt_pk_bf16_f32 v63, v82, v93
	ds_write_b16 v137, v63
	v_mul_f32_e32 v63, v82, v62
	v_fmac_f32_e32 v58, v59, v75
	v_mul_f32_e32 v59, v72, v74
	v_cvt_pk_bf16_f32 v63, v63, v93
	v_fmac_f32_e32 v59, v68, v77
	ds_write_b16 v138, v63
	v_cvt_pk_bf16_f32 v63, v76, v93
	v_mul_f32_e32 v62, v76, v62
	v_fmac_f32_e32 v59, v64, v78
	ds_write_b16 v139, v63
	v_cvt_pk_bf16_f32 v62, v62, v93
	ds_read_b32 v63, v141
	v_fmac_f32_e32 v59, v60, v75
	v_mul_f32_e32 v60, v73, v74
	v_fmac_f32_e32 v60, v69, v77
	v_fmac_f32_e32 v60, v65, v78
	v_fmac_f32_e32 v60, v61, v75
	ds_write_b16 v140, v62
	v_cvt_pk_bf16_f32 v61, v70, v93
	ds_write_b16 v142, v61
	s_waitcnt lgkmcnt(2)
	v_mul_f32_e32 v61, v70, v63
	v_cvt_pk_bf16_f32 v61, v61, v93
	ds_write_b16 v143, v61
	v_cvt_pk_bf16_f32 v61, v58, v93
	v_mul_f32_e32 v58, v58, v63
	ds_write_b16 v144, v61
	v_cvt_pk_bf16_f32 v58, v58, v93
	ds_write_b16 v145, v58
	v_cvt_pk_bf16_f32 v58, v59, v93
	ds_write_b16 v146, v58
	v_mul_f32_e32 v58, v59, v63
	v_cvt_pk_bf16_f32 v58, v58, v93
	ds_write_b16 v147, v58
	v_cvt_pk_bf16_f32 v58, v60, v93
	ds_write_b16 v148, v58
	v_mul_f32_e32 v58, v60, v63
	v_cvt_pk_bf16_f32 v58, v58, v93
	ds_write_b16 v149, v58
	s_and_saveexec_b64 s[52:53], s[6:7]
	s_cbranch_execz .LBB0_431
	ds_read_b32 v58, v120
	s_waitcnt lgkmcnt(0)
	v_cvt_pk_bf16_f32 v58, v58, v93
	ds_write_b16 v119, v58 offset:8704
